# E32: E27 + ret_prompt also touches the next chunk's q' rows (LDS-DMA L2 prefetch), whose late loads gate the next chunk-top wait
# baseline (speedup 1.0000x reference)
.LBB0_1724:
	s_lshl_b32 s1, s37, 7
	s_or_b32 s0, s1, s34
	v_or_b32_e32 v66, s0, v195
	v_readlane_b32 s40, v254, 11
	v_lshl_or_b32 v100, v66, 10, v234
	v_readlane_b32 s42, v254, 13
	v_readlane_b32 s43, v254, 14
	v_or_b32_e32 v68, s0, v197
	v_or_b32_e32 v74, s0, v198
	v_lshl_add_u64 v[66:67], v[100:101], 1, s[42:43]
	v_lshl_or_b32 v100, v68, 10, v234
	v_lshl_add_u64 v[70:71], v[100:101], 1, s[42:43]
	v_lshl_or_b32 v100, v74, 10, v234
	v_or_b32_e32 v76, s0, v199
	v_lshl_add_u64 v[74:75], v[100:101], 1, s[42:43]
	v_lshl_or_b32 v100, v76, 10, v234
	v_or_b32_e32 v82, s0, v200
	v_lshl_add_u64 v[78:79], v[100:101], 1, s[42:43]
	v_lshl_or_b32 v100, v82, 10, v234
	v_or_b32_e32 v84, s0, v201
	v_lshl_add_u64 v[82:83], v[100:101], 1, s[42:43]
	v_lshl_or_b32 v100, v84, 10, v234
	v_or_b32_e32 v91, s0, v202
	v_lshl_add_u64 v[92:93], v[100:101], 1, s[42:43]
	v_lshl_or_b32 v100, v91, 10, v234
	v_add_u32_e32 v91, s0, v203
	global_load_dwordx4 v[66:69], v[66:67], off
	s_nop 0
	global_load_dwordx4 v[70:73], v[70:71], off
	s_nop 0
	global_load_dwordx4 v[74:77], v[74:75], off
	s_nop 0
	global_load_dwordx4 v[78:81], v[78:79], off
	s_nop 0
	global_load_dwordx4 v[82:85], v[82:83], off
	s_nop 0
	global_load_dwordx4 v[156:159], v[92:93], off
	v_lshl_add_u64 v[92:93], v[100:101], 1, s[42:43]
	v_lshl_or_b32 v100, v91, 10, v234
	v_or_b32_e32 v91, s1, v204
	v_lshl_add_u64 v[110:111], v[100:101], 1, s[42:43]
	v_lshlrev_b32_e32 v91, 1, v91
	global_load_dwordx4 v[190:193], v[92:93], off
	global_load_dwordx4 v[242:245], v[110:111], off
	v_add_lshl_u32 v92, v205, s1, 1
	global_load_dwordx4 v[246:249], v91, s[22:23]
	global_load_dwordx4 v[110:113], v92, s[22:23]
	v_mov_b32_e32 v91, v213
	v_mov_b32_e32 v92, v212
	s_mov_b32 s1, 0
	v_readlane_b32 s41, v254, 12
	v_readlane_b32 s44, v254, 15
	v_readlane_b32 s45, v254, 16
	v_readlane_b32 s46, v254, 17
	v_readlane_b32 s47, v254, 18
	s_waitcnt vmcnt(9)
	ds_write_b128 v208, v[66:69] offset:33792
	s_waitcnt vmcnt(8)
	ds_write_b128 v214, v[70:73] offset:33792
	s_waitcnt vmcnt(7)
	ds_write_b128 v208, v[74:77] offset:50688
	s_waitcnt vmcnt(6)
	ds_write_b128 v215, v[78:81] offset:33792
	s_waitcnt vmcnt(5)
	ds_write_b128 v209, v[82:85] offset:33792
	s_waitcnt vmcnt(4)
	ds_write_b128 v216, v[156:159] offset:33792
	s_waitcnt vmcnt(3)
	ds_write_b128 v209, v[190:193] offset:50688
	s_waitcnt vmcnt(2)
	ds_write_b128 v217, v[242:245] offset:33792
	s_waitcnt vmcnt(1)
	ds_write_b128 v218, v[246:249]
	s_waitcnt vmcnt(0)
	ds_write_b128 v219, v[110:113]
	s_waitcnt lgkmcnt(0)
	s_barrier
	s_cmp_ge_u32 s37, 15
	s_cbranch_scc1 .Lmy_rp_nopf
	v_readlane_b32 s98, v254, 11
	v_readlane_b32 s99, v254, 12
	s_mov_b32 m0, 0x1d000
	s_lshl_b32 s100, s37, 7
	s_add_i32 s100, s100, 0x80
	s_or_b32 s101, s100, s34
	v_or_b32_e32 v242, s101, v195
	v_lshl_or_b32 v242, v242, 10, v234
	v_lshlrev_b32_e32 v242, 1, v242
	global_load_lds_dword v242, s[42:43]
	global_load_lds_dword v242, s[98:99]
	v_or_b32_e32 v242, s101, v197
	v_lshl_or_b32 v242, v242, 10, v234
	v_lshlrev_b32_e32 v242, 1, v242
	global_load_lds_dword v242, s[42:43]
	global_load_lds_dword v242, s[98:99]
	v_or_b32_e32 v242, s101, v198
	v_lshl_or_b32 v242, v242, 10, v234
	v_lshlrev_b32_e32 v242, 1, v242
	global_load_lds_dword v242, s[42:43]
	global_load_lds_dword v242, s[98:99]
	v_or_b32_e32 v242, s101, v199
	v_lshl_or_b32 v242, v242, 10, v234
	v_lshlrev_b32_e32 v242, 1, v242
	global_load_lds_dword v242, s[42:43]
	global_load_lds_dword v242, s[98:99]
	v_or_b32_e32 v242, s101, v200
	v_lshl_or_b32 v242, v242, 10, v234
	v_lshlrev_b32_e32 v242, 1, v242
	global_load_lds_dword v242, s[42:43]
	global_load_lds_dword v242, s[98:99]
	v_or_b32_e32 v242, s101, v201
	v_lshl_or_b32 v242, v242, 10, v234
	v_lshlrev_b32_e32 v242, 1, v242
	global_load_lds_dword v242, s[42:43]
	global_load_lds_dword v242, s[98:99]
	v_or_b32_e32 v242, s101, v202
	v_lshl_or_b32 v242, v242, 10, v234
	v_lshlrev_b32_e32 v242, 1, v242
	global_load_lds_dword v242, s[42:43]
	global_load_lds_dword v242, s[98:99]
	v_add_u32_e32 v242, s101, v203
	v_lshl_or_b32 v242, v242, 10, v234
	v_lshlrev_b32_e32 v242, 1, v242
	global_load_lds_dword v242, s[42:43]
	global_load_lds_dword v242, s[98:99]
	v_or_b32_e32 v242, s100, v204
	v_lshlrev_b32_e32 v242, 1, v242
	global_load_lds_dword v242, s[22:23]
	v_add_lshl_u32 v242, v205, s100, 1
	global_load_lds_dword v242, s[22:23]
